# out-proj row exchange: L1 invalidate dropped (the exchanged partial sums are read with L1-bypassing sc1 loads; no other cross-workgroup data is read before the next grid barrier)
# speedup vs baseline: 1.0096x; 1.0096x over previous
.LBB0_841:
	s_or_b64 exec, exec, s[38:39]
	s_nop 0
	s_waitcnt vmcnt(0)

.LBB0_1028:
	s_or_b64 exec, exec, s[16:17]
	s_nop 0
	s_waitcnt vmcnt(0)
